# mix_b sgu sample unit: the two gate loads issued with the iteration's other loads, serial vmcnt(0) round trips replaced by counted waits
# speedup vs baseline: 1.0197x; 1.0002x over previous
.LBB0_1303:
	v_add_u32_e32 v7, s7, v10
	v_ashrrev_i32_e32 v8, 8, v7
	v_ashrrev_i32_e32 v9, 31, v8
	v_lshl_add_u64 v[12:13], v[8:9], 0, v[0:1]
	v_lshlrev_b64 v[12:13], 9, v[12:13]
	v_lshl_add_u64 v[24:25], s[64:65], 0, v[12:13]
	v_add_u32_e32 v12, v8, v0
	v_ashrrev_i32_e32 v13, 31, v12
	v_lshl_add_u64 v[12:13], v[12:13], 2, s[66:67]
	global_load_dword v7, v[12:13], off
	s_nop 0
	global_load_dwordx4 v[12:15], v[24:25], off offset:16
	global_load_dwordx4 v[16:19], v[24:25], off
	global_load_dwordx4 v[20:23], v[24:25], off offset:48
	s_nop 0
	global_load_dwordx4 v[24:27], v[24:25], off offset:32
	ds_read2st64_b32 v[28:29], v6 offset1:4
	v_add_u32_e32 v8, s6, v8
	v_ashrrev_i32_e32 v9, 31, v8
	v_mad_i64_i32 v[98:99], s[0:1], v8, s36, v[2:3]
	global_load_ushort v100, v[98:99], off
	global_load_ushort v101, v[98:99], off offset:1024
	s_addk_i32 s7, 0x200
	s_cmpk_lg_i32 s7, 0x1000
	s_waitcnt vmcnt(4) lgkmcnt(0)
	v_fmac_f32_e32 v7, v16, v28
	v_fmac_f32_e32 v7, v17, v29
	ds_read2st64_b32 v[16:17], v6 offset0:8 offset1:12
	s_waitcnt lgkmcnt(0)
	v_fmac_f32_e32 v7, v18, v16
	v_fmac_f32_e32 v7, v19, v17
	ds_read2st64_b32 v[16:17], v6 offset0:16 offset1:20
	s_waitcnt lgkmcnt(0)
	v_fmac_f32_e32 v7, v12, v16
	v_fmac_f32_e32 v7, v13, v17
	ds_read2st64_b32 v[12:13], v6 offset0:24 offset1:28
	s_waitcnt lgkmcnt(0)
	v_fmac_f32_e32 v7, v14, v12
	v_fmac_f32_e32 v7, v15, v13
	ds_read2st64_b32 v[12:13], v6 offset0:32 offset1:36
	s_waitcnt vmcnt(2) lgkmcnt(0)
	v_pk_mul_f32 v[12:13], v[24:25], v[12:13]
	s_nop 0
	v_add_f32_e32 v7, v7, v12
	v_add_f32_e32 v7, v7, v13
	ds_read2st64_b32 v[12:13], v6 offset0:40 offset1:44
	s_waitcnt lgkmcnt(0)
	v_pk_mul_f32 v[12:13], v[26:27], v[12:13]
	s_nop 0
	v_add_f32_e32 v7, v7, v12
	v_add_f32_e32 v7, v7, v13
	ds_read2st64_b32 v[12:13], v6 offset0:48 offset1:52
	s_waitcnt lgkmcnt(0)
	v_pk_mul_f32 v[12:13], v[20:21], v[12:13]
	s_nop 0
	v_add_f32_e32 v7, v7, v12
	v_add_f32_e32 v7, v7, v13
	ds_read2st64_b32 v[12:13], v6 offset0:56 offset1:60
	s_waitcnt lgkmcnt(0)
	v_pk_mul_f32 v[12:13], v[22:23], v[12:13]
	s_nop 0
	v_add_f32_e32 v7, v7, v12
	v_add_f32_e32 v7, v7, v13
	v_lshlrev_b64 v[8:9], 11, v[8:9]
	v_lshl_add_u64 v[8:9], v[4:5], 0, v[8:9]
	s_waitcnt vmcnt(0)
	v_lshlrev_b32_e32 v11, 16, v100
	v_mul_f32_e32 v7, v7, v11
	v_lshlrev_b32_e32 v11, 16, v101
	v_mul_f32_e32 v7, v7, v11
	v_cvt_pk_bf16_f32 v7, v7, v1
	global_store_short v[8:9], v7, off
	s_cbranch_scc1 .LBB0_1303
	s_add_i32 s10, s10, s78
	s_cmpk_lt_i32 s10, 0x150
	s_barrier
	s_cbranch_scc1 .LBB0_1302
